# prep section C (K.K^T, K.Q^T tiles + decay/beta epilogue) rewritten by hand: batched LDS reads, branch-free select epilogue
# speedup vs baseline: 1.0094x; 1.0094x over previous
.LBB0_316:
	v_ashrrev_i32_e32 v181, 3, v135
	s_lshr_b32 s0, s23, 7
	v_and_b32_e32 v183, -2, v181
	v_and_b32_e32 v1, 15, v135
	s_lshl_b32 s0, s0, 6
	v_add3_u32 v60, s7, -3, v183
	v_lshlrev_b32_e32 v3, 3, v1
	s_and_b32 s0, s0, 0x180
	v_max_i32_e32 v16, -2, v60
	v_add_u32_e32 v62, s7, v183
	v_or_b32_e32 v61, s0, v3
	v_add_u32_e32 v16, 2, v16
	v_mov_b32_e32 v17, v0
	v_max_i32_e32 v20, 0, v62
	v_mov_b32_e32 v21, v0
	v_lshlrev_b32_e32 v28, 1, v61
	v_mov_b32_e32 v29, v0
	v_max_i32_e32 v12, -1, v60
	v_lshl_add_u64 v[16:17], s[4:5], 0, v[16:17]
	v_lshl_add_u64 v[20:21], s[4:5], 0, v[20:21]
	v_max_i32_e32 v26, -4, v60
	v_lshl_add_u64 v[24:25], s[12:13], 0, v[28:29]
	v_max_i32_e32 v8, 0, v60
	v_mov_b32_e32 v9, v0
	v_add_u32_e32 v12, 1, v12
	v_mov_b32_e32 v13, v0
	v_lshlrev_b64 v[36:37], 12, v[16:17]
	v_lshlrev_b64 v[40:41], 12, v[20:21]
	v_add_u32_e32 v26, 4, v26
	v_mov_b32_e32 v27, v0
	v_lshl_add_u64 v[8:9], s[4:5], 0, v[8:9]
	v_lshl_add_u64 v[12:13], s[4:5], 0, v[12:13]
	v_lshl_add_u64 v[16:17], v[24:25], 0, v[36:37]
	v_lshl_add_u64 v[20:21], v[24:25], 0, v[40:41]
	v_lshl_add_u64 v[26:27], s[4:5], 0, v[26:27]
	s_waitcnt lgkmcnt(0)
	s_barrier
	v_lshlrev_b64 v[30:31], 12, v[8:9]
	v_lshlrev_b64 v[32:33], 12, v[12:13]
	global_load_dwordx4 v[16:19], v[16:17], off
	v_lshlrev_b64 v[44:45], 12, v[26:27]
	global_load_dwordx4 v[20:23], v[20:21], off
	v_lshl_add_u64 v[8:9], v[24:25], 0, v[30:31]
	v_lshl_add_u64 v[12:13], v[24:25], 0, v[32:33]
	v_lshl_add_u64 v[24:25], v[24:25], 0, v[44:45]
	global_load_dwordx4 v[24:27], v[24:25], off
	v_mov_b32_e32 v47, v0
	global_load_dwordx4 v[8:11], v[8:9], off
	v_or_b32_e32 v46, 0x400, v28
	global_load_dwordx4 v[12:15], v[12:13], off
	v_lshl_add_u64 v[54:55], s[12:13], 0, v[40:41]
	v_lshl_add_u64 v[40:41], v[54:55], 0, v[46:47]
	v_lshl_add_u64 v[58:59], s[12:13], 0, v[44:45]
	v_lshl_add_u64 v[48:49], s[12:13], 0, v[30:31]
	v_lshl_add_u64 v[50:51], s[12:13], 0, v[32:33]
	v_lshl_add_u64 v[52:53], s[12:13], 0, v[36:37]
	global_load_dwordx4 v[40:43], v[40:41], off
	v_lshl_add_u64 v[44:45], v[58:59], 0, v[46:47]
	v_lshl_add_u64 v[28:29], v[48:49], 0, v[46:47]
	v_lshl_add_u64 v[32:33], v[50:51], 0, v[46:47]
	v_lshl_add_u64 v[36:37], v[52:53], 0, v[46:47]
	global_load_dwordx4 v[44:47], v[44:45], off
	v_cmp_gt_i32_e64 s[4:5], 0, v62
	v_readlane_b32 s34, v251, 51
	v_lshl_or_b32 v3, s6, 7, v3
	v_readlane_b32 s35, v251, 52
	v_or_b32_e32 v3, 0x400, v3
	v_cmp_gt_i32_e64 s[6:7], -4, v60
	global_load_dwordx4 v[28:31], v[28:29], off
	v_mov_b32_e32 v57, v0
	v_lshlrev_b32_e32 v56, 1, v3
	v_lshl_add_u64 v[48:49], v[48:49], 0, v[56:57]
	v_cmp_gt_i32_e32 vcc, 0, v60
	v_cmp_gt_i32_e64 s[0:1], -1, v60
	v_cmp_gt_i32_e64 s[2:3], -2, v60
	s_movk_i32 s25, 0x4000
	global_load_dwordx4 v[32:35], v[32:33], off
	v_lshl_add_u64 v[50:51], v[50:51], 0, v[56:57]
	global_load_dwordx4 v[36:39], v[36:37], off
	s_nop 0
	global_load_dwordx4 v[104:107], v[48:49], off
	global_load_dwordx4 v[108:111], v[50:51], off
	s_mov_b64 s[28:29], 0x2000
	s_movk_i32 s26, 0x6000
	s_mov_b64 s[30:31], 0x6000
	v_add_u32_e32 v201, 64, v2
	v_lshlrev_b32_e32 v197, 4, v1
	v_lshrrev_b32_e32 v198, 5, v135
	v_bfe_u32 v200, v135, 2, 2
	s_waitcnt vmcnt(11)
	v_cndmask_b32_e64 v161, v16, 0, s[2:3]
	v_cndmask_b32_e64 v129, v17, 0, s[2:3]
	s_waitcnt vmcnt(10)
	v_cndmask_b32_e64 v163, v20, 0, s[4:5]
	v_cndmask_b32_e64 v131, v21, 0, s[4:5]
	v_lshlrev_b32_e32 v20, 2, v61
	v_mov_b32_e32 v21, v0
	v_cndmask_b32_e64 v125, v22, 0, s[4:5]
	v_cndmask_b32_e64 v117, v23, 0, s[4:5]
	v_lshl_add_u64 v[22:23], s[34:35], 0, v[20:21]
	s_waitcnt vmcnt(9)
	v_cndmask_b32_e64 v202, v26, 0, s[6:7]
	v_add_co_u32_e64 v26, s[8:9], s62, v22
	v_cndmask_b32_e64 v203, v27, 0, s[6:7]
	s_nop 0
	v_addc_co_u32_e64 v27, s[8:9], 0, v23, s[8:9]
	s_waitcnt vmcnt(8)
	v_cndmask_b32_e64 v165, v8, 0, vcc
	v_cndmask_b32_e64 v118, v9, 0, vcc
	s_waitcnt vmcnt(7)
	v_cndmask_b32_e64 v133, v12, 0, s[0:1]
	v_cndmask_b32_e64 v127, v13, 0, s[0:1]
	v_lshl_add_u64 v[8:9], v[52:53], 0, v[56:57]
	v_lshl_add_u64 v[12:13], v[54:55], 0, v[56:57]
	v_lshl_add_u64 v[16:17], v[58:59], 0, v[56:57]
	v_add_co_u32_e64 v48, s[8:9], s25, v22
	v_cndmask_b32_e64 v119, v10, 0, vcc
	v_cndmask_b32_e64 v120, v11, 0, vcc
	v_cndmask_b32_e64 v121, v14, 0, s[0:1]
	v_cndmask_b32_e64 v113, v15, 0, s[0:1]
	v_cndmask_b32_e64 v123, v18, 0, s[2:3]
	v_cndmask_b32_e64 v115, v19, 0, s[2:3]
	global_load_dwordx4 v[8:11], v[8:9], off
	v_cndmask_b32_e64 v196, v24, 0, s[6:7]
	global_load_dwordx4 v[12:15], v[12:13], off
	v_cndmask_b32_e64 v199, v25, 0, s[6:7]
	global_load_dwordx4 v[16:19], v[16:17], off
	s_nop 0
	global_load_dwordx4 v[72:75], v20, s[34:35]
	global_load_dwordx4 v[88:91], v20, s[34:35] offset:16
	v_lshl_add_u64 v[24:25], v[22:23], 0, s[28:29]
	v_addc_co_u32_e64 v49, s[8:9], 0, v23, s[8:9]
	global_load_dwordx4 v[76:79], v[26:27], off
	global_load_dwordx4 v[92:95], v[24:25], off offset:16
	v_lshl_add_u64 v[24:25], v[22:23], 0, s[48:49]
	v_add_co_u32_e64 v52, s[8:9], s26, v22
	global_load_dwordx4 v[96:99], v[24:25], off offset:16
	s_nop 0
	v_addc_co_u32_e64 v53, s[8:9], 0, v23, s[8:9]
	v_lshl_add_u64 v[24:25], v[22:23], 0, s[30:31]
	global_load_dwordx4 v[80:83], v[52:53], off
	global_load_dwordx4 v[100:103], v[24:25], off offset:16
	s_mov_b64 s[8:9], 0x2800
	s_waitcnt vmcnt(16)
	v_cndmask_b32_e64 v180, v40, 0, s[4:5]
	v_cndmask_b32_e64 v187, v41, 0, s[4:5]
	v_cndmask_b32_e64 v191, v42, 0, s[4:5]
	v_cndmask_b32_e64 v195, v43, 0, s[4:5]
	global_load_dwordx4 v[40:43], v20, s[34:35] offset:2048
	global_load_dwordx4 v[56:59], v20, s[34:35] offset:2064
	v_lshl_add_u64 v[20:21], v[22:23], 0, s[8:9]
	s_mov_b64 s[8:9], 0x4800
	s_waitcnt vmcnt(17)
	v_cndmask_b32_e64 v172, v44, 0, s[6:7]
	v_cndmask_b32_e64 v174, v45, 0, s[6:7]
	v_cndmask_b32_e64 v175, v46, 0, s[6:7]
	v_cndmask_b32_e64 v176, v47, 0, s[6:7]
	global_load_dwordx4 v[44:47], v[26:27], off offset:2048
	v_lshl_add_u64 v[24:25], v[22:23], 0, s[8:9]
	global_load_dwordx4 v[84:87], v[48:49], off
	s_nop 0
	global_load_dwordx4 v[48:51], v[48:49], off offset:2048
	s_nop 0
	global_load_dwordx4 v[64:67], v[20:21], off offset:16
	global_load_dwordx4 v[68:71], v[24:25], off offset:16
	s_waitcnt vmcnt(18)
	v_cndmask_b32_e64 v148, v105, 0, vcc
	v_cndmask_b32_e64 v168, v104, 0, vcc
	v_lshlrev_b32_e32 v104, 16, v120
	v_and_b32_e32 v105, 0xffff0000, v120
	v_lshlrev_b32_e32 v112, 16, v113
	v_and_b32_e32 v113, 0xffff0000, v113
	v_lshlrev_b32_e32 v114, 16, v115
	v_and_b32_e32 v115, 0xffff0000, v115
	v_lshlrev_b32_e32 v116, 16, v117
	v_and_b32_e32 v117, 0xffff0000, v117
	s_mov_b64 s[8:9], 0x6800
	v_cndmask_b32_e64 v140, v107, 0, vcc
	v_lshl_add_u64 v[20:21], v[22:23], 0, s[8:9]
	v_cndmask_b32_e64 v144, v106, 0, vcc
	global_load_dwordx4 v[52:55], v[52:53], off offset:2048
	s_nop 0
	global_load_dwordx4 v[60:63], v[20:21], off offset:16
	v_cndmask_b32_e64 v177, v28, 0, vcc
	v_cndmask_b32_e64 v184, v29, 0, vcc
	v_cndmask_b32_e64 v188, v30, 0, vcc
	v_cndmask_b32_e64 v192, v31, 0, vcc
	v_cndmask_b32_e64 v178, v32, 0, s[0:1]
	v_cndmask_b32_e64 v185, v33, 0, s[0:1]
	v_cndmask_b32_e64 v189, v34, 0, s[0:1]
	v_cndmask_b32_e64 v193, v35, 0, s[0:1]
	s_waitcnt vmcnt(19)
	v_cndmask_b32_e64 v141, v111, 0, s[0:1]
	v_cndmask_b32_e64 v145, v110, 0, s[0:1]
	v_cndmask_b32_e64 v149, v109, 0, s[0:1]
	v_cndmask_b32_e64 v169, v108, 0, s[0:1]
	v_xor_b32_e32 v108, 1, v182
	v_lshlrev_b32_e32 v120, 16, v121
	v_and_b32_e32 v121, 0xffff0000, v121
	v_lshlrev_b32_e32 v122, 16, v123
	v_and_b32_e32 v123, 0xffff0000, v123
	v_lshlrev_b32_e32 v124, 16, v125
	v_and_b32_e32 v125, 0xffff0000, v125
	v_lshlrev_b32_e32 v130, 16, v131
	v_and_b32_e32 v131, 0xffff0000, v131
	v_cndmask_b32_e64 v179, v36, 0, s[2:3]
	v_cndmask_b32_e64 v186, v37, 0, s[2:3]
	v_cndmask_b32_e64 v190, v38, 0, s[2:3]
	v_cndmask_b32_e64 v194, v39, 0, s[2:3]
	s_waitcnt vmcnt(18)
	v_cndmask_b32_e64 v142, v11, 0, s[2:3]
	v_cndmask_b32_e64 v146, v10, 0, s[2:3]
	s_waitcnt vmcnt(17)
	v_cndmask_b32_e64 v171, v12, 0, s[4:5]
	v_lshlrev_b32_e32 v12, 2, v3
	v_cndmask_b32_e64 v151, v13, 0, s[4:5]
	s_waitcnt vmcnt(14)
	v_pk_fma_f32 v[104:105], v[90:91], v[104:105], 0 op_sel_hi:[1,1,0]
	v_mov_b32_e32 v13, v0
	v_lshl_add_u64 v[20:21], s[34:35], 0, v[12:13]
	v_cndmask_b32_e64 v147, v14, 0, s[4:5]
	s_waitcnt vmcnt(12)
	v_pk_fma_f32 v[104:105], v[94:95], v[112:113], v[104:105]
	v_add_co_u32_e32 v14, vcc, s62, v20
	v_cndmask_b32_e64 v143, v15, 0, s[4:5]
	s_waitcnt vmcnt(11)
	v_pk_fma_f32 v[104:105], v[98:99], v[114:115], v[104:105]
	v_addc_co_u32_e32 v15, vcc, 0, v21, vcc
	v_cndmask_b32_e64 v137, v18, 0, s[6:7]
	s_waitcnt vmcnt(9)
	v_pk_fma_f32 v[104:105], v[102:103], v[116:117], v[104:105]
	v_add_co_u32_e32 v18, vcc, s25, v20
	v_mul_f32_e32 v3, 0xbfb8aa3b, v105
	v_exp_f32_e32 v107, v3
	v_mul_f32_e32 v3, 0xbfb8aa3b, v104
	v_exp_f32_e32 v106, v3
	v_cndmask_b32_e64 v136, v19, 0, s[6:7]
	v_addc_co_u32_e32 v19, vcc, 0, v21, vcc
	v_pk_add_f32 v[2:3], v[106:107], 1.0 op_sel_hi:[1,0]
	v_cndmask_b32_e64 v150, v9, 0, s[2:3]
	s_nop 0
	v_cndmask_b32_e64 v170, v8, 0, s[2:3]
	v_cndmask_b32_e64 v138, v17, 0, s[6:7]
	v_cndmask_b32_e64 v139, v16, 0, s[6:7]
	global_load_dwordx4 v[8:11], v12, s[34:35] offset:16
	global_load_dwordx4 v[24:27], v12, s[34:35]
	v_lshl_add_u64 v[12:13], v[20:21], 0, s[28:29]
	v_lshl_add_u64 v[16:17], v[20:21], 0, s[48:49]
	v_lshl_add_u64 v[22:23], v[20:21], 0, s[30:31]
	v_add_co_u32_e32 v20, vcc, s26, v20
	s_nop 0
	s_nop 0
	v_addc_co_u32_e32 v21, vcc, 0, v21, vcc
	v_cmp_lt_i32_e32 vcc, v108, v201
	v_pk_fma_f32 v[90:91], v[90:91], v[112:113], 0 op_sel_hi:[1,1,0]
	s_mov_b32 s4, 0x358637bd
	v_cndmask_b32_e32 v108, v182, v108, vcc
	v_lshlrev_b32_e32 v173, 2, v108
	s_nop 0
	s_nop 0
	s_nop 0
	s_nop 0
	s_nop 0
	s_nop 0
	s_nop 0
	s_nop 0
	s_nop 0
	s_nop 0
	v_rcp_f32_e32 v3, v3
	s_nop 0
	s_nop 0
	s_nop 0
	s_nop 0
	s_nop 0
	s_nop 0
	v_lshlrev_b32_e32 v106, 16, v119
	v_and_b32_e32 v107, 0xffff0000, v119
	v_pk_fma_f32 v[106:107], v[88:89], v[106:107], 0 op_sel_hi:[1,1,0]
	s_nop 0
	v_pk_fma_f32 v[106:107], v[92:93], v[120:121], v[106:107]
	s_nop 0
	v_pk_fma_f32 v[106:107], v[96:97], v[122:123], v[106:107]
	v_rcp_f32_e32 v2, v2
	v_pk_fma_f32 v[106:107], v[100:101], v[124:125], v[106:107]
	v_pk_fma_f32 v[90:91], v[94:95], v[114:115], v[90:91]
	v_mul_f32_e32 v108, 0xbfb8aa3b, v106
	v_mul_f32_e32 v109, 0xbfb8aa3b, v107
	v_exp_f32_e32 v108, v108
	v_exp_f32_e32 v109, v109
	v_pk_fma_f32 v[90:91], v[98:99], v[116:117], v[90:91]
	v_lshlrev_b32_e32 v94, 16, v203
	v_and_b32_e32 v95, 0xffff0000, v203
	v_pk_add_f32 v[108:109], v[108:109], 1.0 op_sel_hi:[1,0]
	v_pk_fma_f32 v[94:95], v[102:103], v[94:95], v[90:91]
	s_nop 0
	s_nop 0
	s_nop 0
	s_nop 0
	s_nop 0
	s_nop 0
	s_nop 0
	s_nop 0
	s_nop 0
	s_nop 0
	s_nop 0
	s_nop 0
	v_rcp_f32_e32 v109, v109
	s_nop 0
	s_nop 0
	s_nop 0
	s_nop 0
	s_nop 0
	s_nop 0
	v_lshlrev_b32_e32 v110, 16, v118
	v_and_b32_e32 v111, 0xffff0000, v118
	v_lshlrev_b32_e32 v126, 16, v127
	v_and_b32_e32 v127, 0xffff0000, v127
	v_pk_fma_f32 v[110:111], v[74:75], v[110:111], 0 op_sel_hi:[1,1,0]
	v_lshlrev_b32_e32 v128, 16, v129
	v_and_b32_e32 v129, 0xffff0000, v129
	v_pk_fma_f32 v[110:111], v[78:79], v[126:127], v[110:111]
	s_nop 0
	s_waitcnt vmcnt(7)
	v_pk_fma_f32 v[110:111], v[86:87], v[128:129], v[110:111]
	s_nop 0
	v_pk_fma_f32 v[110:111], v[82:83], v[130:131], v[110:111]
	v_rcp_f32_e32 v108, v108
	v_mul_f32_e32 v118, 0xbfb8aa3b, v110
	v_mul_f32_e32 v119, 0xbfb8aa3b, v111
	v_exp_f32_e32 v118, v118
	v_exp_f32_e32 v119, v119
	v_mul_f32_e32 v90, 0xbfb8aa3b, v95
	v_exp_f32_e32 v91, v90
	v_mul_f32_e32 v90, 0xbfb8aa3b, v94
	v_pk_add_f32 v[118:119], v[118:119], 1.0 op_sel_hi:[1,0]
	v_exp_f32_e32 v90, v90
	s_nop 0
	s_nop 0
	s_nop 0
	s_nop 0
	s_nop 0
	s_nop 0
	s_nop 0
	s_nop 0
	s_nop 0
	s_nop 0
	s_nop 0
	s_nop 0
	v_rcp_f32_e32 v119, v119
	s_nop 0
	s_nop 0
	s_nop 0
	s_nop 0
	s_nop 0
	v_lshlrev_b32_e32 v164, 16, v165
	v_and_b32_e32 v165, 0xffff0000, v165
	s_nop 0
	v_lshlrev_b32_e32 v132, 16, v133
	v_and_b32_e32 v133, 0xffff0000, v133
	v_pk_fma_f32 v[164:165], v[72:73], v[164:165], 0 op_sel_hi:[1,1,0]
	v_lshlrev_b32_e32 v160, 16, v161
	v_and_b32_e32 v161, 0xffff0000, v161
	v_pk_fma_f32 v[164:165], v[76:77], v[132:133], v[164:165]
	v_lshlrev_b32_e32 v162, 16, v163
	v_and_b32_e32 v163, 0xffff0000, v163
	v_pk_fma_f32 v[164:165], v[84:85], v[160:161], v[164:165]
	s_nop 0
	v_pk_fma_f32 v[164:165], v[80:81], v[162:163], v[164:165]
	s_nop 0
	v_mul_f32_e32 v204, 0xbfb8aa3b, v164
	v_mul_f32_e32 v205, 0xbfb8aa3b, v165
	v_exp_f32_e32 v204, v204
	v_exp_f32_e32 v205, v205
	v_rcp_f32_e32 v118, v118
	v_pk_fma_f32 v[88:89], v[88:89], v[120:121], 0 op_sel_hi:[1,1,0]
	v_pk_fma_f32 v[74:75], v[74:75], v[126:127], 0 op_sel_hi:[1,1,0]
	v_pk_add_f32 v[204:205], v[204:205], 1.0 op_sel_hi:[1,0]
	v_pk_fma_f32 v[88:89], v[92:93], v[122:123], v[88:89]
	s_nop 0
	s_nop 0
	v_pk_fma_f32 v[88:89], v[96:97], v[124:125], v[88:89]
	v_lshlrev_b32_e32 v92, 16, v202
	v_and_b32_e32 v93, 0xffff0000, v202
	s_nop 0
	s_nop 0
	s_nop 0
	s_nop 0
	s_nop 0
	s_nop 0
	s_nop 0
	s_nop 0
	s_nop 0
	s_nop 0
	v_rcp_f32_e32 v205, v205
	v_pk_fma_f32 v[92:93], v[100:101], v[92:93], v[88:89]
	s_nop 0
	s_nop 0
	s_nop 0
	s_nop 0
	s_nop 0
	s_nop 0
	s_nop 0
	s_nop 0
	v_pk_add_f32 v[98:99], v[90:91], 1.0 op_sel_hi:[1,0]
	v_mul_f32_e32 v88, 0xbfb8aa3b, v92
	s_nop 0
	s_nop 0
	v_mul_f32_e32 v89, 0xbfb8aa3b, v93
	v_exp_f32_e32 v88, v88
	v_exp_f32_e32 v89, v89
	s_nop 0
	s_nop 0
	s_nop 0
	s_nop 0
	s_nop 0
	s_nop 0
	s_nop 0
	s_nop 0
	s_nop 0
	s_nop 0
	v_rcp_f32_e32 v99, v99
	v_pk_fma_f32 v[74:75], v[78:79], v[128:129], v[74:75]
	s_nop 0
	s_nop 0
	s_nop 0
	s_nop 0
	s_nop 0
	s_nop 0
	s_nop 0
	s_nop 0
	v_pk_add_f32 v[96:97], v[88:89], 1.0 op_sel_hi:[1,0]
	v_rcp_f32_e32 v98, v98
	s_nop 0
	s_nop 0
	v_pk_mul_f32 v[88:89], v[94:95], v[98:99]
	v_pk_fma_f32 v[74:75], v[86:87], v[130:131], v[74:75]
	v_lshlrev_b32_e32 v78, 16, v199
	s_nop 0
	s_nop 0
	s_nop 0
	s_nop 0
	s_nop 0
	s_nop 0
	s_nop 0
	s_nop 0
	s_nop 0
	v_and_b32_e32 v79, 0xffff0000, v199
	v_pk_fma_f32 v[74:75], v[82:83], v[78:79], v[74:75]
	s_nop 0
	v_mul_f32_e32 v78, 0xbfb8aa3b, v74
	v_mul_f32_e32 v79, 0xbfb8aa3b, v75
	v_rcp_f32_e32 v97, v97
	s_nop 0
	v_exp_f32_e32 v78, v78
	v_exp_f32_e32 v79, v79
	s_nop 0
	s_nop 0
	s_nop 0
	s_nop 0
	s_nop 0
	v_pk_add_f32 v[78:79], v[78:79], 1.0 op_sel_hi:[1,0]
	s_nop 0
	s_nop 0
	s_nop 0
	s_nop 0
	v_rcp_f32_e32 v96, v96
	s_nop 0
	v_pk_mul_f32 v[82:83], v[92:93], v[96:97]
	v_pk_fma_f32 v[72:73], v[72:73], v[132:133], 0 op_sel_hi:[1,1,0]
	s_nop 0
	s_nop 0
	s_nop 0
	s_nop 0
	s_nop 0
	v_pk_fma_f32 v[72:73], v[76:77], v[160:161], v[72:73]
	s_nop 0
	s_nop 0
	v_pk_fma_f32 v[72:73], v[84:85], v[162:163], v[72:73]
	v_lshlrev_b32_e32 v76, 16, v196
	v_and_b32_e32 v77, 0xffff0000, v196
	s_nop 0
	v_pk_fma_f32 v[72:73], v[80:81], v[76:77], v[72:73]
	s_nop 0
	v_mul_f32_e32 v76, 0xbfb8aa3b, v72
	v_mul_f32_e32 v77, 0xbfb8aa3b, v73
	v_exp_f32_e32 v76, v76
	v_exp_f32_e32 v77, v77
	s_nop 0
	v_rcp_f32_e32 v79, v79
	s_nop 0
	s_nop 0
	s_nop 0
	s_nop 0
	v_pk_add_f32 v[76:77], v[76:77], 1.0 op_sel_hi:[1,0]
	s_nop 0
	s_nop 0
	s_nop 0
	s_nop 0
	s_nop 0
	s_nop 0
	v_rcp_f32_e32 v78, v78
	s_nop 0
	v_pk_mul_f32 v[80:81], v[74:75], v[78:79]
	s_nop 0
	s_nop 0
	s_nop 0
	s_nop 0
	s_nop 0
	s_nop 0
	s_nop 0
	s_nop 0
	s_nop 0
	s_nop 0
	v_rcp_f32_e32 v77, v77
	v_rcp_f32_e32 v204, v204
	s_nop 0
	s_nop 0
	s_nop 0
	s_nop 0
	s_nop 0
	s_nop 0
	s_nop 0
	s_nop 0
	v_rcp_f32_e32 v76, v76
	v_pk_mul_f32 v[90:91], v[164:165], v[204:205]
	v_pk_mul_f32 v[84:85], v[72:73], v[76:77]
	v_pk_mul_f32 v[110:111], v[110:111], v[118:119]
	v_pk_mul_f32 v[102:103], v[90:91], v[90:91]
	v_pk_mul_f32 v[72:73], v[84:85], v[84:85]
	v_pk_mul_f32 v[118:119], v[110:111], v[110:111]
	v_pk_mul_f32 v[74:75], v[80:81], v[80:81]
	v_mov_b32_e32 v76, v72
	v_mov_b32_e32 v77, v102
	v_mov_b32_e32 v102, v73
	v_pk_mul_f32 v[106:107], v[106:107], v[108:109]
	v_pk_add_f32 v[72:73], v[76:77], v[102:103]
	v_mov_b32_e32 v76, v74
	v_mov_b32_e32 v77, v118
	v_pk_mul_f32 v[108:109], v[106:107], v[106:107]
	v_pk_mul_f32 v[86:87], v[82:83], v[82:83]
	v_pk_add_f32 v[72:73], v[76:77], v[72:73]
	v_mov_b32_e32 v118, v75
	v_pk_mul_f32 v[2:3], v[104:105], v[2:3]
	v_pk_add_f32 v[72:73], v[118:119], v[72:73]
	v_mov_b32_e32 v74, v86
	v_mov_b32_e32 v75, v108
	v_pk_mul_f32 v[104:105], v[2:3], v[2:3]
	v_pk_mul_f32 v[94:95], v[88:89], v[88:89]
	v_pk_add_f32 v[72:73], v[74:75], v[72:73]
	v_mov_b32_e32 v108, v87
	v_pk_add_f32 v[72:73], v[108:109], v[72:73]
	v_mov_b32_e32 v74, v94
	v_mov_b32_e32 v75, v104
	v_pk_add_f32 v[72:73], v[74:75], v[72:73]
	v_mov_b32_e32 v104, v95
	v_pk_add_f32 v[72:73], v[104:105], v[72:73]
	ds_bpermute_b32 v75, v173, v73
	ds_bpermute_b32 v74, v173, v72
	v_xor_b32_e32 v76, 2, v182
	v_cmp_lt_i32_e32 vcc, v76, v201
	s_mov_b32 s0, 0x27ffffc
	v_and_b32_e32 v77, 48, v197
	v_cndmask_b32_e32 v76, v182, v76, vcc
	v_lshlrev_b32_e32 v118, 2, v76
	s_waitcnt lgkmcnt(0)
	v_pk_add_f32 v[72:73], v[72:73], v[74:75]
	ds_bpermute_b32 v75, v118, v73
	ds_bpermute_b32 v74, v118, v72
	v_xor_b32_e32 v76, 4, v182
	v_cmp_lt_i32_e32 vcc, v76, v201
	v_add_u32_e32 v92, 0, v197
	s_add_i32 s25, 0, 0x20500
	v_cndmask_b32_e32 v76, v182, v76, vcc
	v_lshlrev_b32_e32 v119, 2, v76
	s_waitcnt lgkmcnt(0)
	v_pk_add_f32 v[72:73], v[72:73], v[74:75]
	ds_bpermute_b32 v75, v119, v73
	ds_bpermute_b32 v74, v119, v72
	v_xor_b32_e32 v76, 8, v182
	v_cmp_lt_i32_e32 vcc, v76, v201
	global_load_dwordx4 v[28:31], v[14:15], off
	s_nop 0
	global_load_dwordx4 v[12:15], v[12:13], off offset:16
	v_cndmask_b32_e32 v76, v182, v76, vcc
	v_lshlrev_b32_e32 v120, 2, v76
	s_waitcnt lgkmcnt(0)
	v_pk_add_f32 v[72:73], v[72:73], v[74:75]
	ds_bpermute_b32 v75, v120, v73
	ds_bpermute_b32 v74, v120, v72
	v_and_or_b32 v76, v198, s0, v200
	v_lshl_or_b32 v121, v76, 6, v77
	v_mad_u64_u32 v[76:77], s[0:1], v183, s54, v[92:93]
	s_waitcnt lgkmcnt(0)
	v_pk_add_f32 v[72:73], v[72:73], v[74:75]
	global_load_dwordx4 v[32:35], v[18:19], off
	s_nop 0
	global_load_dwordx4 v[16:19], v[16:17], off offset:16
	v_pk_add_f32 v[86:87], v[72:73], s[4:5] op_sel_hi:[1,0]
	global_load_dwordx4 v[36:39], v[20:21], off
	s_nop 0
	global_load_dwordx4 v[20:23], v[22:23], off offset:16
	v_mul_f32_e32 v72, 0x4b800000, v87
	v_cmp_gt_f32_e32 vcc, s51, v87
	v_lshl_add_u32 v77, v183, 2, s25
	s_add_u32 s0, s10, s16
	v_cndmask_b32_e32 v72, v87, v72, vcc
	v_rsq_f32_e32 v72, v72
	v_mul_f32_e32 v87, 0x4b800000, v86
	s_addc_u32 s1, s11, s17
	v_lshlrev_b32_e32 v100, 16, v194
	v_mul_f32_e32 v73, 0x45800000, v72
	v_cndmask_b32_e32 v72, v72, v73, vcc
	v_mul_f32_e32 v72, 0x3db504f3, v72
	v_pk_mul_f32 v[90:91], v[90:91], v[72:73] op_sel_hi:[1,0]
	v_pk_mul_f32 v[94:95], v[110:111], v[72:73] op_sel_hi:[1,0]
	v_pk_mul_f32 v[96:97], v[106:107], v[72:73] op_sel_hi:[1,0]
	v_pk_mul_f32 v[2:3], v[2:3], v[72:73] op_sel_hi:[1,0]
	v_cvt_pk_bf16_f32 v72, v90, v91
	v_cvt_pk_bf16_f32 v73, v94, v95
	v_cvt_pk_bf16_f32 v74, v96, v97
	v_cvt_pk_bf16_f32 v75, v2, v3
	ds_write_b128 v76, v[72:75] offset:17408
	ds_read_b32 v74, v77
	v_cmp_gt_f32_e32 vcc, s51, v86
	v_and_or_b32 v72, v181, 14, v121
	v_lshlrev_b32_e32 v72, 3, v72
	v_cndmask_b32_e32 v86, v86, v87, vcc
	s_waitcnt lgkmcnt(0)
	v_mul_f32_e32 v74, 0x3fb8aa3b, v74
	v_exp_f32_e32 v98, v74
	v_rsq_f32_e32 v86, v86
	v_ashrrev_i32_e32 v73, 31, v72
	v_lshl_add_u64 v[78:79], v[72:73], 1, s[0:1]
	v_pk_mul_f32 v[72:73], v[98:99], v[90:91] op_sel_hi:[0,1]
	v_pk_mul_f32 v[74:75], v[98:99], v[94:95] op_sel_hi:[0,1]
	v_cvt_pk_bf16_f32 v72, v72, v73
	v_cvt_pk_bf16_f32 v73, v74, v75
	v_pk_mul_f32 v[74:75], v[98:99], v[96:97] op_sel_hi:[0,1]
	v_pk_mul_f32 v[2:3], v[98:99], v[2:3] op_sel_hi:[0,1]
	v_cvt_pk_bf16_f32 v74, v74, v75
	v_cvt_pk_bf16_f32 v75, v2, v3
	v_mul_f32_e32 v2, 0x45800000, v86
	v_cndmask_b32_e32 v2, v86, v2, vcc
	v_mul_f32_e32 v2, 0x3db504f3, v2
	v_pk_mul_f32 v[86:87], v[84:85], v[2:3] op_sel_hi:[1,0]
	v_pk_mul_f32 v[84:85], v[80:81], v[2:3] op_sel_hi:[1,0]
	v_pk_mul_f32 v[82:83], v[82:83], v[2:3] op_sel_hi:[1,0]
	v_pk_mul_f32 v[80:81], v[88:89], v[2:3] op_sel_hi:[1,0]
	v_lshlrev_b32_e32 v2, 16, v192
	v_and_b32_e32 v3, 0xffff0000, v192
	v_lshlrev_b32_e32 v98, 16, v193
	v_and_b32_e32 v99, 0xffff0000, v193
	v_pk_fma_f32 v[2:3], v[58:59], v[2:3], 0 op_sel_hi:[1,1,0]
	v_and_b32_e32 v101, 0xffff0000, v194
	s_waitcnt vmcnt(11)
	v_pk_fma_f32 v[2:3], v[66:67], v[98:99], v[2:3]
	v_lshlrev_b32_e32 v102, 16, v195
	v_and_b32_e32 v103, 0xffff0000, v195
	s_waitcnt vmcnt(10)
	v_pk_fma_f32 v[2:3], v[70:71], v[100:101], v[2:3]
	v_or_b32_e32 v77, 1, v181
	s_waitcnt vmcnt(8)
	v_pk_fma_f32 v[94:95], v[62:63], v[102:103], v[2:3]
	v_cvt_pk_bf16_f32 v88, v86, v87
	v_mul_f32_e32 v2, 0xbfb8aa3b, v95
	v_exp_f32_e32 v97, v2
	v_mul_f32_e32 v2, 0xbfb8aa3b, v94
	v_exp_f32_e32 v96, v2
	v_mad_u64_u32 v[2:3], s[2:3], v77, s54, v[92:93]
	v_cvt_pk_bf16_f32 v89, v84, v85
	v_pk_add_f32 v[92:93], v[96:97], 1.0 op_sel_hi:[1,0]
	v_cvt_pk_bf16_f32 v90, v82, v83
	s_nop 0
	s_nop 0
	v_cvt_pk_bf16_f32 v91, v80, v81
	ds_write_b128 v2, v[88:91] offset:17408
	s_nop 0
	s_nop 0
	s_nop 0
	s_nop 0
	s_nop 0
	s_nop 0
	s_nop 0
	s_nop 0
	s_nop 0
	s_nop 0
	v_rcp_f32_e32 v89, v93
	s_nop 0
	s_nop 0
	s_nop 0
	s_nop 0
	s_nop 0
	s_nop 0
	v_lshlrev_b32_e32 v90, 16, v188
	v_and_b32_e32 v91, 0xffff0000, v188
	v_lshlrev_b32_e32 v106, 16, v189
	v_and_b32_e32 v107, 0xffff0000, v189
	v_pk_fma_f32 v[90:91], v[56:57], v[90:91], 0 op_sel_hi:[1,1,0]
	v_lshlrev_b32_e32 v108, 16, v190
	v_and_b32_e32 v109, 0xffff0000, v190
	v_pk_fma_f32 v[90:91], v[64:65], v[106:107], v[90:91]
	v_lshlrev_b32_e32 v110, 16, v191
	v_and_b32_e32 v111, 0xffff0000, v191
	v_pk_fma_f32 v[90:91], v[68:69], v[108:109], v[90:91]
	s_nop 0
	v_pk_fma_f32 v[96:97], v[60:61], v[110:111], v[90:91]
	s_nop 0
	v_mul_f32_e32 v90, 0xbfb8aa3b, v96
	v_mul_f32_e32 v91, 0xbfb8aa3b, v97
	v_exp_f32_e32 v90, v90
	v_exp_f32_e32 v91, v91
	v_rcp_f32_e32 v88, v92
	s_nop 0
	v_pk_mul_f32 v[88:89], v[94:95], v[88:89]
	v_and_b32_e32 v113, 0xffff0000, v185
	v_pk_add_f32 v[104:105], v[90:91], 1.0 op_sel_hi:[1,0]
	v_lshlrev_b32_e32 v114, 16, v186
	s_nop 0
	s_nop 0
	s_nop 0
	s_nop 0
	s_nop 0
	s_nop 0
	s_nop 0
	s_nop 0
	s_nop 0
	s_nop 0
	s_nop 0
	s_nop 0
	v_rcp_f32_e32 v93, v105
	s_nop 0
	s_nop 0
	s_nop 0
	s_nop 0
	s_nop 0
	s_nop 0
	v_lshlrev_b32_e32 v94, 16, v184
	v_and_b32_e32 v95, 0xffff0000, v184
	v_lshlrev_b32_e32 v112, 16, v185
	v_pk_fma_f32 v[94:95], v[42:43], v[94:95], 0 op_sel_hi:[1,1,0]
	v_and_b32_e32 v115, 0xffff0000, v186
	v_pk_fma_f32 v[94:95], v[46:47], v[112:113], v[94:95]
	v_lshlrev_b32_e32 v116, 16, v187
	v_and_b32_e32 v117, 0xffff0000, v187
	v_pk_fma_f32 v[94:95], v[50:51], v[114:115], v[94:95]
	s_nop 0
	v_pk_fma_f32 v[122:123], v[54:55], v[116:117], v[94:95]
	s_nop 0
	v_mul_f32_e32 v94, 0xbfb8aa3b, v122
	v_mul_f32_e32 v95, 0xbfb8aa3b, v123
	v_exp_f32_e32 v94, v94
	v_exp_f32_e32 v95, v95
	v_rcp_f32_e32 v92, v104
	s_nop 0
	v_pk_mul_f32 v[92:93], v[96:97], v[92:93]
	v_and_b32_e32 v127, 0xffff0000, v178
	v_pk_add_f32 v[124:125], v[94:95], 1.0 op_sel_hi:[1,0]
	v_lshlrev_b32_e32 v128, 16, v179
	s_nop 0
	s_nop 0
	s_nop 0
	s_nop 0
	s_nop 0
	s_nop 0
	s_nop 0
	s_nop 0
	s_nop 0
	s_nop 0
	s_nop 0
	s_nop 0
	v_rcp_f32_e32 v97, v125
	s_nop 0
	s_nop 0
	s_nop 0
	s_nop 0
	s_nop 0
	s_nop 0
	v_lshlrev_b32_e32 v104, 16, v177
	v_and_b32_e32 v105, 0xffff0000, v177
	v_lshlrev_b32_e32 v126, 16, v178
	v_pk_fma_f32 v[104:105], v[40:41], v[104:105], 0 op_sel_hi:[1,1,0]
	v_and_b32_e32 v129, 0xffff0000, v179
	v_pk_fma_f32 v[104:105], v[44:45], v[126:127], v[104:105]
	v_lshlrev_b32_e32 v130, 16, v180
	v_and_b32_e32 v131, 0xffff0000, v180
	v_pk_fma_f32 v[104:105], v[48:49], v[128:129], v[104:105]
	s_nop 0
	v_pk_fma_f32 v[132:133], v[52:53], v[130:131], v[104:105]
	s_nop 0
	v_mul_f32_e32 v104, 0xbfb8aa3b, v132
	v_mul_f32_e32 v105, 0xbfb8aa3b, v133
	v_exp_f32_e32 v104, v104
	v_exp_f32_e32 v105, v105
	v_rcp_f32_e32 v96, v124
	s_nop 0
	v_pk_mul_f32 v[96:97], v[122:123], v[96:97]
	v_pk_fma_f32 v[58:59], v[58:59], v[98:99], 0 op_sel_hi:[1,1,0]
	v_pk_add_f32 v[160:161], v[104:105], 1.0 op_sel_hi:[1,0]
	v_pk_fma_f32 v[58:59], v[66:67], v[100:101], v[58:59]
	s_nop 0
	s_nop 0
	v_pk_fma_f32 v[58:59], v[70:71], v[102:103], v[58:59]
	v_lshlrev_b32_e32 v66, 16, v176
	v_and_b32_e32 v67, 0xffff0000, v176
	s_nop 0
	s_nop 0
	s_nop 0
	s_nop 0
	s_nop 0
	s_nop 0
	s_nop 0
	s_nop 0
	s_nop 0
	s_nop 0
	v_pk_fma_f32 v[62:63], v[62:63], v[66:67], v[58:59]
	v_rcp_f32_e32 v123, v161
	s_nop 0
	v_mul_f32_e32 v58, 0xbfb8aa3b, v63
	s_nop 0
	s_nop 0
	v_exp_f32_e32 v59, v58
	v_mul_f32_e32 v58, 0xbfb8aa3b, v62
	s_nop 0
	v_exp_f32_e32 v58, v58
	s_nop 0
	s_nop 0
	s_nop 0
	s_nop 0
	v_pk_add_f32 v[66:67], v[58:59], 1.0 op_sel_hi:[1,0]
	v_pk_fma_f32 v[56:57], v[56:57], v[106:107], 0 op_sel_hi:[1,1,0]
	s_nop 0
	s_nop 0
	v_pk_fma_f32 v[56:57], v[64:65], v[108:109], v[56:57]
	v_lshlrev_b32_e32 v64, 16, v175
	v_pk_fma_f32 v[56:57], v[68:69], v[110:111], v[56:57]
	s_nop 0
	s_nop 0
	s_nop 0
	s_nop 0
	s_nop 0
	s_nop 0
	s_nop 0
	s_nop 0
	s_nop 0
	s_nop 0
	v_and_b32_e32 v65, 0xffff0000, v175
	v_rcp_f32_e32 v67, v67
	s_nop 0
	v_pk_fma_f32 v[60:61], v[60:61], v[64:65], v[56:57]
	s_nop 0
	s_nop 0
	v_mul_f32_e32 v56, 0xbfb8aa3b, v60
	v_mul_f32_e32 v57, 0xbfb8aa3b, v61
	s_nop 0
	v_exp_f32_e32 v56, v56
	v_exp_f32_e32 v57, v57
	s_nop 0
	s_nop 0
	s_nop 0
	s_nop 0
	v_pk_add_f32 v[64:65], v[56:57], 1.0 op_sel_hi:[1,0]
	v_rcp_f32_e32 v66, v66
	s_nop 0
	s_nop 0
	v_pk_mul_f32 v[56:57], v[62:63], v[66:67]
	v_pk_fma_f32 v[42:43], v[42:43], v[112:113], 0 op_sel_hi:[1,1,0]
	v_pk_fma_f32 v[40:41], v[40:41], v[126:127], 0 op_sel_hi:[1,1,0]
	s_nop 0
	s_nop 0
	s_nop 0
	s_nop 0
	s_nop 0
	s_nop 0
	s_nop 0
	s_nop 0
	s_nop 0
	v_pk_fma_f32 v[42:43], v[46:47], v[114:115], v[42:43]
	v_lshlrev_b32_e32 v46, 16, v174
	v_pk_fma_f32 v[42:43], v[50:51], v[116:117], v[42:43]
	v_and_b32_e32 v47, 0xffff0000, v174
	v_pk_fma_f32 v[42:43], v[54:55], v[46:47], v[42:43]
	s_nop 0
	v_mul_f32_e32 v46, 0xbfb8aa3b, v42
	v_mul_f32_e32 v47, 0xbfb8aa3b, v43
	v_rcp_f32_e32 v65, v65
	s_nop 0
	v_exp_f32_e32 v46, v46
	v_exp_f32_e32 v47, v47
	s_nop 0
	s_nop 0
	s_nop 0
	s_nop 0
	s_nop 0
	v_pk_add_f32 v[46:47], v[46:47], 1.0 op_sel_hi:[1,0]
	s_nop 0
	s_nop 0
	s_nop 0
	s_nop 0
	v_rcp_f32_e32 v64, v64
	s_nop 0
	v_pk_mul_f32 v[50:51], v[60:61], v[64:65]
	v_pk_fma_f32 v[40:41], v[44:45], v[128:129], v[40:41]
	s_nop 0
	s_nop 0
	s_nop 0
	s_nop 0
	s_nop 0
	v_pk_fma_f32 v[40:41], v[48:49], v[130:131], v[40:41]
	v_lshlrev_b32_e32 v44, 16, v172
	v_and_b32_e32 v45, 0xffff0000, v172
	s_nop 0
	s_nop 0
	v_pk_fma_f32 v[40:41], v[52:53], v[44:45], v[40:41]
	s_nop 0
	v_mul_f32_e32 v44, 0xbfb8aa3b, v40
	v_mul_f32_e32 v45, 0xbfb8aa3b, v41
	v_exp_f32_e32 v44, v44
	v_exp_f32_e32 v45, v45
	s_nop 0
	s_nop 0
	v_rcp_f32_e32 v47, v47
	s_nop 0
	s_nop 0
	s_nop 0
	v_pk_add_f32 v[44:45], v[44:45], 1.0 op_sel_hi:[1,0]
	s_nop 0
	s_nop 0
	s_nop 0
	s_nop 0
	s_nop 0
	s_nop 0
	s_nop 0
	v_rcp_f32_e32 v46, v46
	s_nop 0
	s_nop 0
	s_nop 0
	s_nop 0
	s_nop 0
	s_nop 0
	s_nop 0
	s_nop 0
	s_nop 0
	s_nop 0
	v_rcp_f32_e32 v45, v45
	v_rcp_f32_e32 v122, v160
	s_nop 0
	s_nop 0
	s_nop 0
	s_nop 0
	s_nop 0
	s_nop 0
	s_nop 0
	s_nop 0
	v_rcp_f32_e32 v44, v44
	v_pk_mul_f32 v[58:59], v[132:133], v[122:123]
	v_pk_mul_f32 v[44:45], v[40:41], v[44:45]
	v_pk_mul_f32 v[70:71], v[58:59], v[58:59]
	v_pk_mul_f32 v[46:47], v[42:43], v[46:47]
	v_pk_mul_f32 v[40:41], v[44:45], v[44:45]
	v_pk_mul_f32 v[104:105], v[96:97], v[96:97]
	v_pk_mul_f32 v[42:43], v[46:47], v[46:47]
	v_mov_b32_e32 v48, v40
	v_mov_b32_e32 v49, v70
	v_mov_b32_e32 v70, v41
	v_pk_add_f32 v[40:41], v[48:49], v[70:71]
	v_mov_b32_e32 v48, v42
	v_mov_b32_e32 v49, v104
	v_pk_mul_f32 v[94:95], v[92:93], v[92:93]
	v_pk_mul_f32 v[54:55], v[50:51], v[50:51]
	v_pk_add_f32 v[40:41], v[48:49], v[40:41]
	v_mov_b32_e32 v104, v43
	v_pk_add_f32 v[40:41], v[104:105], v[40:41]
	v_mov_b32_e32 v42, v54
	v_mov_b32_e32 v43, v94
	v_pk_mul_f32 v[90:91], v[88:89], v[88:89]
	v_pk_mul_f32 v[62:63], v[56:57], v[56:57]
	v_pk_add_f32 v[40:41], v[42:43], v[40:41]
	v_mov_b32_e32 v94, v55
	v_pk_add_f32 v[40:41], v[94:95], v[40:41]
	v_mov_b32_e32 v42, v62
	v_mov_b32_e32 v43, v90
	v_pk_add_f32 v[40:41], v[42:43], v[40:41]
	v_mov_b32_e32 v90, v63
	v_pk_add_f32 v[40:41], v[90:91], v[40:41]
	v_lshl_add_u32 v3, v77, 2, s25
	ds_bpermute_b32 v43, v173, v41
	ds_bpermute_b32 v42, v173, v40
	ds_read_b32 v3, v3
	s_mov_b32 s2, 0x13800000
	v_add_co_u32_e32 v48, vcc, s2, v78
	s_waitcnt lgkmcnt(1)
	v_pk_add_f32 v[42:43], v[40:41], v[42:43]
	v_addc_co_u32_e32 v49, vcc, 0, v79, vcc
	s_waitcnt lgkmcnt(0)
	v_mul_f32_e32 v3, 0x3fb8aa3b, v3
	ds_bpermute_b32 v53, v118, v43
	ds_bpermute_b32 v52, v118, v42
	global_store_dwordx4 v[48:49], v[72:75], off nt
	v_exp_f32_e32 v48, v3
	v_and_or_b32 v3, v77, 15, v121
	v_lshlrev_b32_e32 v66, 16, v144
	s_waitcnt lgkmcnt(0)
	v_pk_add_f32 v[52:53], v[42:43], v[52:53]
	v_pk_mul_f32 v[40:41], v[48:49], v[86:87] op_sel_hi:[0,1]
	v_pk_mul_f32 v[54:55], v[48:49], v[84:85] op_sel_hi:[0,1]
	v_cvt_pk_bf16_f32 v40, v40, v41
	v_cvt_pk_bf16_f32 v41, v54, v55
	ds_bpermute_b32 v55, v119, v53
	ds_bpermute_b32 v54, v119, v52
	v_pk_mul_f32 v[42:43], v[48:49], v[82:83] op_sel_hi:[0,1]
	v_pk_mul_f32 v[48:49], v[48:49], v[80:81] op_sel_hi:[0,1]
	v_cvt_pk_bf16_f32 v42, v42, v43
	v_cvt_pk_bf16_f32 v43, v48, v49
	s_waitcnt lgkmcnt(0)
	v_pk_add_f32 v[48:49], v[52:53], v[54:55]
	ds_bpermute_b32 v53, v120, v49
	ds_bpermute_b32 v52, v120, v48
	v_lshlrev_b32_e32 v54, 3, v3
	v_ashrrev_i32_e32 v55, 31, v54
	v_lshl_add_u64 v[54:55], v[54:55], 1, s[0:1]
	v_and_b32_e32 v67, 0xffff0000, v144
	s_waitcnt lgkmcnt(0)
	v_pk_add_f32 v[48:49], v[48:49], v[52:53]
	v_add_co_u32_e64 v52, s[0:1], s2, v54
	v_pk_add_f32 v[48:49], v[48:49], s[4:5] op_sel_hi:[1,0]
	s_nop 0
	v_addc_co_u32_e64 v53, s[0:1], 0, v55, s[0:1]
	v_mul_f32_e32 v3, 0x4b800000, v49
	v_cmp_gt_f32_e32 vcc, s51, v49
	global_store_dwordx4 v[52:53], v[40:43], off nt
	s_waitcnt vmcnt(9)
	v_pk_fma_f32 v[66:67], v[8:9], v[66:67], 0 op_sel_hi:[1,1,0]
	v_cndmask_b32_e32 v3, v49, v3, vcc
	v_rsq_f32_e32 v3, v3
	v_and_b32_e32 v73, 0xffff0000, v140
	s_bfe_u32 s28, s24, 0x20006
	s_ashr_i32 s26, s24, 7
	v_mul_f32_e32 v40, 0x45800000, v3
	v_cndmask_b32_e32 v40, v3, v40, vcc
	v_mul_f32_e32 v3, 0x4b800000, v48
	v_cmp_gt_f32_e32 vcc, s51, v48
	v_pk_mul_f32 v[42:43], v[58:59], v[40:41] op_sel_hi:[1,0]
	v_pk_mul_f32 v[52:53], v[96:97], v[40:41] op_sel_hi:[1,0]
	v_cndmask_b32_e32 v3, v48, v3, vcc
	v_rsq_f32_e32 v3, v3
	v_pk_mul_f32 v[54:55], v[92:93], v[40:41] op_sel_hi:[1,0]
	v_pk_mul_f32 v[58:59], v[88:89], v[40:41] op_sel_hi:[1,0]
	v_cvt_pk_bf16_f32 v40, v42, v43
	v_cvt_pk_bf16_f32 v41, v52, v53
	v_cvt_pk_bf16_f32 v42, v54, v55
	v_cvt_pk_bf16_f32 v43, v58, v59
	ds_write_b128 v76, v[40:43]
	v_mul_f32_e32 v40, 0x45800000, v3
	v_cndmask_b32_e32 v48, v3, v40, vcc
	v_pk_mul_f32 v[54:55], v[46:47], v[48:49] op_sel_hi:[1,0]
	v_lshlrev_b32_e32 v46, 16, v168
	v_and_b32_e32 v47, 0xffff0000, v168
	v_lshlrev_b32_e32 v40, 16, v169
	v_and_b32_e32 v41, 0xffff0000, v169
	s_waitcnt vmcnt(8)
	v_pk_fma_f32 v[46:47], v[24:25], v[46:47], 0 op_sel_hi:[1,1,0]
	v_lshlrev_b32_e32 v42, 16, v170
	v_and_b32_e32 v43, 0xffff0000, v170
	s_waitcnt vmcnt(7)
	v_pk_fma_f32 v[46:47], v[28:29], v[40:41], v[46:47]
	v_pk_mul_f32 v[52:53], v[44:45], v[48:49] op_sel_hi:[1,0]
	v_lshlrev_b32_e32 v44, 16, v171
	v_and_b32_e32 v45, 0xffff0000, v171
	s_waitcnt vmcnt(5)
	v_pk_fma_f32 v[46:47], v[32:33], v[42:43], v[46:47]
	v_pk_mul_f32 v[50:51], v[50:51], v[48:49] op_sel_hi:[1,0]
	s_waitcnt vmcnt(3)
	v_pk_fma_f32 v[58:59], v[36:37], v[44:45], v[46:47]
	v_cvt_pk_bf16_f32 v46, v52, v53
	v_mul_f32_e32 v3, 0xbfb8aa3b, v58
	v_exp_f32_e32 v60, v3
	v_mul_f32_e32 v3, 0xbfb8aa3b, v59
	v_exp_f32_e32 v61, v3
	v_cvt_pk_bf16_f32 v47, v54, v55
	v_pk_mul_f32 v[56:57], v[56:57], v[48:49] op_sel_hi:[1,0]
	v_cvt_pk_bf16_f32 v48, v50, v51
	v_pk_add_f32 v[52:53], v[60:61], 1.0 op_sel_hi:[1,0]
	v_cvt_pk_bf16_f32 v49, v56, v57
	s_nop 0
	s_nop 0
	ds_write_b128 v2, v[46:49]
	v_and_b32_e32 v55, 0xffff0000, v148
	s_nop 0
	s_nop 0
	s_nop 0
	s_nop 0
	s_nop 0
	s_nop 0
	s_nop 0
	s_nop 0
	s_nop 0
	v_lshlrev_b32_e32 v54, 16, v148
	v_lshlrev_b32_e32 v46, 16, v149
	v_and_b32_e32 v47, 0xffff0000, v149
	v_pk_fma_f32 v[54:55], v[26:27], v[54:55], 0 op_sel_hi:[1,1,0]
	s_nop 0
	v_lshlrev_b32_e32 v48, 16, v150
	v_and_b32_e32 v49, 0xffff0000, v150
	v_pk_fma_f32 v[54:55], v[30:31], v[46:47], v[54:55]
	v_lshlrev_b32_e32 v50, 16, v151
	v_and_b32_e32 v51, 0xffff0000, v151
	v_pk_fma_f32 v[54:55], v[34:35], v[48:49], v[54:55]
	v_rcp_f32_e32 v53, v53
	v_pk_fma_f32 v[60:61], v[38:39], v[50:51], v[54:55]
	s_nop 0
	v_mul_f32_e32 v54, 0xbfb8aa3b, v60
	v_mul_f32_e32 v55, 0xbfb8aa3b, v61
	v_exp_f32_e32 v54, v54
	v_exp_f32_e32 v55, v55
	s_nop 0
	s_nop 0
	s_nop 0
	s_nop 0
	s_nop 0
	v_pk_add_f32 v[62:63], v[54:55], 1.0 op_sel_hi:[1,0]
	s_nop 0
	s_nop 0
	s_nop 0
	s_nop 0
	v_rcp_f32_e32 v52, v52
	s_nop 0
	v_pk_mul_f32 v[64:65], v[58:59], v[52:53]
	s_nop 0
	s_nop 0
	s_nop 0
	s_nop 0
	s_nop 0
	s_nop 0
	s_nop 0
	s_nop 0
	v_lshlrev_b32_e32 v52, 16, v145
	v_and_b32_e32 v53, 0xffff0000, v145
	s_nop 0
	v_lshlrev_b32_e32 v54, 16, v146
	v_and_b32_e32 v55, 0xffff0000, v146
	v_pk_fma_f32 v[66:67], v[12:13], v[52:53], v[66:67]
	s_nop 0
	v_lshlrev_b32_e32 v56, 16, v147
	v_and_b32_e32 v57, 0xffff0000, v147
	v_pk_fma_f32 v[66:67], v[16:17], v[54:55], v[66:67]
	v_rcp_f32_e32 v59, v63
	s_waitcnt vmcnt(2)
	v_pk_fma_f32 v[66:67], v[20:21], v[56:57], v[66:67]
	s_nop 0
	v_mul_f32_e32 v68, 0xbfb8aa3b, v66
	v_mul_f32_e32 v69, 0xbfb8aa3b, v67
	v_exp_f32_e32 v68, v68
	v_exp_f32_e32 v69, v69
	s_nop 0
	s_nop 0
	s_nop 0
	s_nop 0
	v_pk_add_f32 v[68:69], v[68:69], 1.0 op_sel_hi:[1,0]
	s_nop 0
	s_nop 0
	s_nop 0
	s_nop 0
	s_nop 0
	v_rcp_f32_e32 v58, v62
	s_nop 0
	s_nop 0
	s_nop 0
	v_pk_mul_f32 v[62:63], v[60:61], v[58:59]
	s_nop 0
	s_nop 0
	s_nop 0
	s_nop 0
	s_nop 0
	v_lshlrev_b32_e32 v72, 16, v140
	v_lshlrev_b32_e32 v58, 16, v141
	v_and_b32_e32 v59, 0xffff0000, v141
	v_pk_fma_f32 v[72:73], v[10:11], v[72:73], 0 op_sel_hi:[1,1,0]
	s_nop 0
	v_lshlrev_b32_e32 v60, 16, v142
	v_and_b32_e32 v61, 0xffff0000, v142
	v_pk_fma_f32 v[72:73], v[14:15], v[58:59], v[72:73]
	s_nop 0
	v_lshlrev_b32_e32 v70, 16, v143
	v_and_b32_e32 v71, 0xffff0000, v143
	v_pk_fma_f32 v[72:73], v[18:19], v[60:61], v[72:73]
	v_rcp_f32_e32 v69, v69
	v_pk_fma_f32 v[72:73], v[22:23], v[70:71], v[72:73]
	s_nop 0
	v_mul_f32_e32 v74, 0xbfb8aa3b, v73
	v_exp_f32_e32 v75, v74
	v_mul_f32_e32 v74, 0xbfb8aa3b, v72
	v_exp_f32_e32 v74, v74
	s_nop 0
	s_nop 0
	s_nop 0
	s_nop 0
	s_nop 0
	v_pk_add_f32 v[74:75], v[74:75], 1.0 op_sel_hi:[1,0]
	s_nop 0
	s_nop 0
	s_nop 0
	s_nop 0
	v_rcp_f32_e32 v68, v68
	s_nop 0
	v_pk_mul_f32 v[66:67], v[66:67], v[68:69]
	s_nop 0
	s_nop 0
	s_nop 0
	s_nop 0
	s_nop 0
	s_nop 0
	s_nop 0
	s_nop 0
	s_nop 0
	s_nop 0
	v_rcp_f32_e32 v69, v75
	v_pk_fma_f32 v[24:25], v[24:25], v[40:41], 0 op_sel_hi:[1,1,0]
	s_nop 0
	s_nop 0
	s_nop 0
	s_nop 0
	s_nop 0
	s_nop 0
	v_pk_fma_f32 v[24:25], v[28:29], v[42:43], v[24:25]
	s_nop 0
	v_pk_fma_f32 v[24:25], v[32:33], v[44:45], v[24:25]
	v_lshlrev_b32_e32 v28, 16, v139
	v_and_b32_e32 v29, 0xffff0000, v139
	s_nop 0
	v_pk_fma_f32 v[24:25], v[36:37], v[28:29], v[24:25]
	v_rcp_f32_e32 v68, v74
	v_mul_f32_e32 v3, 0xbfb8aa3b, v24
	v_exp_f32_e32 v28, v3
	v_mul_f32_e32 v3, 0xbfb8aa3b, v25
	v_exp_f32_e32 v29, v3
	v_pk_mul_f32 v[32:33], v[72:73], v[68:69]
	v_pk_fma_f32 v[26:27], v[26:27], v[46:47], 0 op_sel_hi:[1,1,0]
	v_cvt_pk_bf16_f32 v43, v32, v33
	v_pk_add_f32 v[28:29], v[28:29], 1.0 op_sel_hi:[1,0]
	v_pk_fma_f32 v[26:27], v[30:31], v[48:49], v[26:27]
	s_nop 0
	s_nop 0
	v_pk_fma_f32 v[26:27], v[34:35], v[50:51], v[26:27]
	v_lshlrev_b32_e32 v30, 16, v138
	v_and_b32_e32 v31, 0xffff0000, v138
	s_nop 0
	s_nop 0
	s_nop 0
	s_nop 0
	s_nop 0
	s_nop 0
	s_nop 0
	s_nop 0
	s_nop 0
	v_pk_fma_f32 v[26:27], v[38:39], v[30:31], v[26:27]
	s_nop 0
	v_mul_f32_e32 v30, 0xbfb8aa3b, v26
	v_mul_f32_e32 v31, 0xbfb8aa3b, v27
	v_rcp_f32_e32 v29, v29
	s_nop 0
	v_exp_f32_e32 v30, v30
	v_exp_f32_e32 v31, v31
	s_nop 0
	s_nop 0
	s_nop 0
	s_nop 0
	s_nop 0
	v_pk_add_f32 v[30:31], v[30:31], 1.0 op_sel_hi:[1,0]
	s_nop 0
	s_nop 0
	s_nop 0
	s_nop 0
	v_rcp_f32_e32 v28, v28
	s_nop 0
	v_pk_mul_f32 v[24:25], v[24:25], v[28:29]
	s_nop 0
	s_nop 0
	s_nop 0
	s_nop 0
	v_pk_fma_f32 v[8:9], v[8:9], v[52:53], 0 op_sel_hi:[1,1,0]
	s_nop 0
	v_pk_fma_f32 v[8:9], v[12:13], v[54:55], v[8:9]
	s_nop 0
	v_pk_fma_f32 v[8:9], v[16:17], v[56:57], v[8:9]
	v_lshlrev_b32_e32 v12, 16, v137
	v_and_b32_e32 v13, 0xffff0000, v137
	s_nop 0
	s_nop 0
	v_pk_fma_f32 v[8:9], v[20:21], v[12:13], v[8:9]
	s_nop 0
	v_mul_f32_e32 v12, 0xbfb8aa3b, v8
	v_mul_f32_e32 v13, 0xbfb8aa3b, v9
	v_exp_f32_e32 v12, v12
	v_exp_f32_e32 v13, v13
	s_nop 0
	v_rcp_f32_e32 v29, v31
	s_nop 0
	s_nop 0
	s_nop 0
	v_pk_add_f32 v[12:13], v[12:13], 1.0 op_sel_hi:[1,0]
	s_nop 0
	s_nop 0
	s_nop 0
	s_nop 0
	s_nop 0
	s_nop 0
	s_nop 0
	v_rcp_f32_e32 v28, v30
	s_nop 0
	s_nop 0
	s_nop 0
	v_pk_mul_f32 v[16:17], v[26:27], v[28:29]
	s_nop 0
	s_nop 0
	v_pk_fma_f32 v[10:11], v[10:11], v[58:59], 0 op_sel_hi:[1,1,0]
	s_nop 0
	v_pk_fma_f32 v[10:11], v[14:15], v[60:61], v[10:11]
	s_nop 0
	s_nop 0
	v_pk_fma_f32 v[10:11], v[18:19], v[70:71], v[10:11]
	v_lshlrev_b32_e32 v14, 16, v136
	v_and_b32_e32 v15, 0xffff0000, v136
	s_nop 0
	v_pk_fma_f32 v[10:11], v[22:23], v[14:15], v[10:11]
	s_nop 0
	v_mul_f32_e32 v14, 0xbfb8aa3b, v11
	v_exp_f32_e32 v15, v14
	v_mul_f32_e32 v14, 0xbfb8aa3b, v10
	v_exp_f32_e32 v14, v14
	v_rcp_f32_e32 v13, v13
	s_nop 0
	s_nop 0
	s_nop 0
	s_nop 0
	s_nop 0
	v_pk_add_f32 v[14:15], v[14:15], 1.0 op_sel_hi:[1,0]
	s_nop 0
	s_nop 0
	s_nop 0
	s_nop 0
	s_nop 0
	v_rcp_f32_e32 v12, v12
	s_nop 0
	s_nop 0
	s_nop 0
	v_pk_mul_f32 v[12:13], v[8:9], v[12:13]
	s_nop 0
	s_nop 0
	s_nop 0
	s_nop 0
	s_nop 0
	s_nop 0
	s_nop 0
	v_rcp_f32_e32 v9, v15
	s_lshl_b32 s29, s28, 4
	s_nop 0
	s_nop 0
	s_nop 0
	s_nop 0
	s_nop 0
	s_nop 0
	s_nop 0
	s_nop 0
	v_rcp_f32_e32 v8, v14
	s_nop 0
	v_pk_mul_f32 v[14:15], v[10:11], v[8:9]
	v_cvt_pk_bf16_f32 v8, v24, v25
	v_cvt_pk_bf16_f32 v9, v16, v17
	v_cvt_pk_bf16_f32 v10, v12, v13
	v_cvt_pk_bf16_f32 v11, v14, v15
	v_and_b32_e32 v3, 48, v134
	ds_write_b128 v2, v[8:11] offset:34816
	s_and_b32 s27, s26, -2
	v_or_b32_e32 v2, s29, v1
	v_add_u32_e32 v48, 0, v3
	v_cvt_pk_bf16_f32 v40, v64, v65
	v_cvt_pk_bf16_f32 v41, v62, v63
	v_cvt_pk_bf16_f32 v42, v66, v67
	v_mad_u32_u24 v55, v2, s54, v48
	v_lshl_or_b32 v59, s27, 4, v1
	ds_write_b128 v76, v[40:43] offset:34816
	s_waitcnt lgkmcnt(0)
	s_barrier
	s_lshr_b32 s0, s24, 6
	s_and_b32 s1, s0, 3
	s_lshr_b32 s2, s0, 2
	s_lshl_b32 s2, s2, 1
	v_lshrrev_b32_e32 v3, 4, v134
	v_mul_u32_u24_e32 v4, 0x110, v1
	v_lshl_add_u32 v4, v3, 4, v4
	s_mul_i32 s3, s1, 0x1100
	s_mul_i32 s4, s2, 0x1100
	v_add_u32_e32 v2, s3, v4
	v_add_u32_e32 v4, s4, v4
	s_lshl_b32 s5, s1, 6
	s_add_u32 s5, s5, 0x20500
	v_lshl_add_u32 v5, v3, 4, s5
	s_lshl_b32 s6, s2, 6
	s_add_u32 s6, s6, 0x20500
	v_lshl_add_u32 v6, v1, 2, s6
	v_mul_u32_u24_e32 v7, 0x110, v1
	v_lshl_add_u32 v7, v3, 4, v7
	s_lshl_b32 s7, s1, 6
	s_add_u32 s7, s7, s4
	s_add_u32 s7, s7, 0xcc00
	v_add_u32_e32 v7, s7, v7
	v_mul_u32_u24_e32 v9, 0x240, v3
	v_lshl_add_u32 v9, v1, 1, v9
	s_mul_i32 s26, s1, 0x900
	s_lshl_b32 s27, s2, 5
	s_add_u32 s26, s26, s27
	s_add_u32 s26, s26, 0x11000
	v_add_u32_e32 v9, s26, v9
	v_lshrrev_b32_e32 v10, 1, v3
	v_lshlrev_b32_e32 v10, 8, v10
	v_lshl_add_u32 v10, v1, 4, v10
	v_and_b32_e32 v11, 1, v3
	v_lshl_add_u32 v10, v11, 3, v10
	s_lshl_b32 s27, s2, 11
	s_lshl_b32 s28, s1, 9
	s_add_u32 s27, s27, s28
	v_add_u32_e32 v10, s27, v10
	s_add_u32 s26, s10, s18
	s_addc_u32 s27, s11, s19
	s_lshl_b32 s28, s2, 4
	s_lshl_b32 s29, s1, 4
	s_sub_i32 s28, s28, s29
	v_lshlrev_b32_e32 v11, 2, v3
	v_sub_u32_e32 v11, v1, v11
	v_add_u32_e32 v11, s28, v11
	v_add_u32_e32 v70, 16, v11
	ds_read_b128 v[60:63], v5
	ds_read_b128 v[64:67], v5 offset:256
	ds_read_b32 v68, v6
	ds_read_b32 v69, v6 offset:64
	ds_read_b128 v[12:15], v2 offset:0
	ds_read_b128 v[28:31], v4 offset:0
	ds_read_b128 v[44:47], v4 offset:17408
	ds_read_b128 v[16:19], v2 offset:64
	ds_read_b128 v[32:35], v4 offset:64
	ds_read_b128 v[48:51], v4 offset:17472
	ds_read_b128 v[20:23], v2 offset:128
	ds_read_b128 v[36:39], v4 offset:128
	ds_read_b128 v[52:55], v4 offset:17536
	ds_read_b128 v[24:27], v2 offset:192
	ds_read_b128 v[40:43], v4 offset:192
	ds_read_b128 v[56:59], v4 offset:17600
	ds_read_b128 v[136:139], v4 offset:4352
	ds_read_b128 v[168:171], v4 offset:21760
	ds_read_b128 v[140:143], v4 offset:4416
	ds_read_b128 v[172:175], v4 offset:21824
	ds_read_b128 v[144:147], v4 offset:4480
	ds_read_b128 v[176:179], v4 offset:21888
	ds_read_b128 v[148:151], v4 offset:4544
	ds_read_b128 v[184:187], v4 offset:21952
	s_waitcnt lgkmcnt(14)
	v_mfma_f32_16x16x32_bf16 v[160:163], v[12:15], v[28:31], 0
	v_mfma_f32_16x16x32_bf16 v[200:203], v[12:15], v[44:47], 0
	s_waitcnt lgkmcnt(14)
	v_mfma_f32_16x16x32_bf16 v[160:163], v[16:19], v[32:35], v[160:163]
	v_mfma_f32_16x16x32_bf16 v[200:203], v[16:19], v[48:51], v[200:203]
	s_waitcnt lgkmcnt(11)
	v_mfma_f32_16x16x32_bf16 v[160:163], v[20:23], v[36:39], v[160:163]
	v_mfma_f32_16x16x32_bf16 v[200:203], v[20:23], v[52:55], v[200:203]
	s_waitcnt lgkmcnt(8)
	v_mfma_f32_16x16x32_bf16 v[160:163], v[24:27], v[40:43], v[160:163]
	v_mfma_f32_16x16x32_bf16 v[200:203], v[24:27], v[56:59], v[200:203]
	s_waitcnt lgkmcnt(6)
	v_mfma_f32_16x16x32_bf16 v[234:237], v[12:15], v[136:139], 0
	v_mfma_f32_16x16x32_bf16 v[238:241], v[12:15], v[168:171], 0
	s_waitcnt lgkmcnt(4)
	v_mfma_f32_16x16x32_bf16 v[234:237], v[16:19], v[140:143], v[234:237]
	v_mfma_f32_16x16x32_bf16 v[238:241], v[16:19], v[172:175], v[238:241]
	s_waitcnt lgkmcnt(2)
	v_mfma_f32_16x16x32_bf16 v[234:237], v[20:23], v[144:147], v[234:237]
	v_mfma_f32_16x16x32_bf16 v[238:241], v[20:23], v[176:179], v[238:241]
	s_waitcnt lgkmcnt(0)
	v_mfma_f32_16x16x32_bf16 v[234:237], v[24:27], v[148:151], v[234:237]
	v_mfma_f32_16x16x32_bf16 v[238:241], v[24:27], v[184:187], v[238:241]
	v_cmp_lt_i32_e64 s[0:1], v11, 0
	v_cmp_lt_i32_e64 s[2:3], v11, 1
	v_cmp_lt_i32_e64 s[4:5], v11, 2
	v_cmp_lt_i32_e64 s[6:7], v11, 3
	v_cmp_lt_i32_e64 s[28:29], v70, 0
	v_cmp_lt_i32_e64 s[30:31], v70, 1
	v_cmp_lt_i32_e64 s[32:33], v70, 2
	v_cmp_lt_i32_e64 s[34:35], v70, 3
	v_sub_f32_e32 v70, v60, v68
	v_sub_f32_e32 v164, v68, v60
	v_sub_f32_e32 v71, v61, v68
	v_sub_f32_e32 v165, v68, v61
	v_sub_f32_e32 v72, v62, v68
	v_sub_f32_e32 v180, v68, v62
	v_sub_f32_e32 v73, v63, v68
	v_sub_f32_e32 v181, v68, v63
	v_mul_f32_e32 v70, 0x3fb8aa3b, v70
	v_mul_f32_e32 v164, 0x3fb8aa3b, v164
	v_mul_f32_e32 v71, 0x3fb8aa3b, v71
	v_mul_f32_e32 v165, 0x3fb8aa3b, v165
	v_mul_f32_e32 v72, 0x3fb8aa3b, v72
	v_mul_f32_e32 v180, 0x3fb8aa3b, v180
	v_mul_f32_e32 v73, 0x3fb8aa3b, v73
	v_mul_f32_e32 v181, 0x3fb8aa3b, v181
	v_exp_f32_e32 v70, v70
	v_exp_f32_e32 v164, v164
	v_exp_f32_e32 v71, v71
	v_exp_f32_e32 v165, v165
	v_exp_f32_e32 v72, v72
	v_exp_f32_e32 v180, v180
	v_exp_f32_e32 v73, v73
	v_exp_f32_e32 v181, v181
	v_mul_f32_e32 v160, v160, v70
	v_mul_f32_e32 v200, v200, v164
	v_mul_f32_e32 v161, v161, v71
	v_mul_f32_e32 v201, v201, v165
	v_mul_f32_e32 v162, v162, v72
	v_mul_f32_e32 v202, v202, v180
	v_mul_f32_e32 v163, v163, v73
	v_mul_f32_e32 v203, v203, v181
	v_mul_f32_e32 v160, v64, v160
	v_mul_f32_e32 v161, v65, v161
	v_mul_f32_e32 v162, v66, v162
	v_mul_f32_e32 v163, v67, v163
	v_cndmask_b32_e64 v160, 0, v160, s[0:1]
	v_cndmask_b32_e64 v200, v200, 0, s[0:1]
	v_cndmask_b32_e64 v161, 0, v161, s[2:3]
	v_cndmask_b32_e64 v201, v201, 0, s[2:3]
	v_cndmask_b32_e64 v162, 0, v162, s[4:5]
	v_cndmask_b32_e64 v202, v202, 0, s[4:5]
	v_cndmask_b32_e64 v163, 0, v163, s[6:7]
	v_cndmask_b32_e64 v203, v203, 0, s[6:7]
	ds_write_b128 v7, v[160:163]
	v_cvt_pk_bf16_f32 v204, v160, v161
	v_cvt_pk_bf16_f32 v205, v162, v163
	ds_write_b16 v9, v204
	ds_write_b16_d16_hi v9, v204 offset:144
	ds_write_b16 v9, v205 offset:288
	ds_write_b16_d16_hi v9, v205 offset:432
	v_cvt_pk_bf16_f32 v200, v200, v201
	v_cvt_pk_bf16_f32 v201, v202, v203
	global_store_dwordx2 v10, v[200:201], s[26:27] nt
	v_sub_f32_e32 v70, v60, v69
	v_sub_f32_e32 v164, v69, v60
	v_sub_f32_e32 v71, v61, v69
	v_sub_f32_e32 v165, v69, v61
	v_sub_f32_e32 v72, v62, v69
	v_sub_f32_e32 v180, v69, v62
	v_sub_f32_e32 v73, v63, v69
	v_sub_f32_e32 v181, v69, v63
	v_mul_f32_e32 v70, 0x3fb8aa3b, v70
	v_mul_f32_e32 v164, 0x3fb8aa3b, v164
	v_mul_f32_e32 v71, 0x3fb8aa3b, v71
	v_mul_f32_e32 v165, 0x3fb8aa3b, v165
	v_mul_f32_e32 v72, 0x3fb8aa3b, v72
	v_mul_f32_e32 v180, 0x3fb8aa3b, v180
	v_mul_f32_e32 v73, 0x3fb8aa3b, v73
	v_mul_f32_e32 v181, 0x3fb8aa3b, v181
	v_exp_f32_e32 v70, v70
	v_exp_f32_e32 v164, v164
	v_exp_f32_e32 v71, v71
	v_exp_f32_e32 v165, v165
	v_exp_f32_e32 v72, v72
	v_exp_f32_e32 v180, v180
	v_exp_f32_e32 v73, v73
	v_exp_f32_e32 v181, v181
	v_mul_f32_e32 v234, v234, v70
	v_mul_f32_e32 v238, v238, v164
	v_mul_f32_e32 v235, v235, v71
	v_mul_f32_e32 v239, v239, v165
	v_mul_f32_e32 v236, v236, v72
	v_mul_f32_e32 v240, v240, v180
	v_mul_f32_e32 v237, v237, v73
	v_mul_f32_e32 v241, v241, v181
	v_mul_f32_e32 v234, v64, v234
	v_mul_f32_e32 v235, v65, v235
	v_mul_f32_e32 v236, v66, v236
	v_mul_f32_e32 v237, v67, v237
	v_cndmask_b32_e64 v234, 0, v234, s[28:29]
	v_cndmask_b32_e64 v238, v238, 0, s[28:29]
	v_cndmask_b32_e64 v235, 0, v235, s[30:31]
	v_cndmask_b32_e64 v239, v239, 0, s[30:31]
	v_cndmask_b32_e64 v236, 0, v236, s[32:33]
	v_cndmask_b32_e64 v240, v240, 0, s[32:33]
	v_cndmask_b32_e64 v237, 0, v237, s[34:35]
	v_cndmask_b32_e64 v241, v241, 0, s[34:35]
	ds_write_b128 v7, v[234:237] offset:4352
	v_cvt_pk_bf16_f32 v246, v234, v235
	v_cvt_pk_bf16_f32 v247, v236, v237
	ds_write_b16 v9, v246 offset:32
	ds_write_b16_d16_hi v9, v246 offset:176
	ds_write_b16 v9, v247 offset:320
	ds_write_b16_d16_hi v9, v247 offset:464
	v_cvt_pk_bf16_f32 v238, v238, v239
	v_cvt_pk_bf16_f32 v239, v240, v241
	global_store_dwordx2 v10, v[238:239], s[26:27] offset:2048 nt
	s_waitcnt lgkmcnt(0)
	s_barrier
	v_readfirstlane_b32 s26, v135
	s_lshr_b32 s26, s26, 6
	s_cmp_eq_u32 s26, 0
	s_cbranch_scc1 .Lpd_inv
	s_cmp_lt_u32 s26, 4
	s_cbranch_scc1 .Lpd_done
	s_lshr_b32 s27, s26, 1
	s_and_b32 s27, s27, 1
	s_and_b32 s28, s26, 1
	s_lshl_b32 s28, s28, 6
	v_and_b32_e32 v4, 63, v135
	v_add_u32_e32 v5, s28, v4
	s_mul_i32 s29, s27, 0x2200
	v_lshl_add_u32 v6, v5, 1, s29
	s_lshl_b32 s30, s27, 7
	s_add_u32 s30, s30, s25
	v_and_b32_e32 v7, 31, v135
	v_lshl_add_u32 v7, v7, 2, s30
	v_mov_b32_e32 v9, s25
	ds_read_b32 v10, v7
	ds_read_b32 v11, v9 offset:252
	ds_read_u16 v136, v6
	ds_read_u16 v137, v6 offset:272
	ds_read_u16 v138, v6 offset:544
	ds_read_u16 v139, v6 offset:816
	ds_read_u16 v140, v6 offset:1088
	ds_read_u16 v141, v6 offset:1360
	ds_read_u16 v142, v6 offset:1632
	ds_read_u16 v143, v6 offset:1904
	ds_read_u16 v144, v6 offset:2176
	ds_read_u16 v145, v6 offset:2448
	ds_read_u16 v146, v6 offset:2720
	ds_read_u16 v147, v6 offset:2992
	ds_read_u16 v148, v6 offset:3264
	ds_read_u16 v149, v6 offset:3536
	ds_read_u16 v150, v6 offset:3808
	ds_read_u16 v151, v6 offset:4080
	ds_read_u16 v184, v6 offset:4352
	ds_read_u16 v185, v6 offset:4624
	ds_read_u16 v186, v6 offset:4896
	ds_read_u16 v187, v6 offset:5168
	ds_read_u16 v188, v6 offset:5440
	ds_read_u16 v189, v6 offset:5712
	ds_read_u16 v190, v6 offset:5984
	ds_read_u16 v191, v6 offset:6256
	ds_read_u16 v192, v6 offset:6528
	ds_read_u16 v193, v6 offset:6800
	ds_read_u16 v194, v6 offset:7072
	ds_read_u16 v195, v6 offset:7344
	ds_read_u16 v196, v6 offset:7616
	ds_read_u16 v197, v6 offset:7888
	ds_read_u16 v198, v6 offset:8160
	ds_read_u16 v199, v6 offset:8432
	v_lshrrev_b32_e32 v2, 4, v5
	v_lshl_add_u32 v2, v2, 1, s27
	v_lshlrev_b32_e32 v2, 10, v2
	v_and_b32_e32 v3, 15, v5
	v_lshl_add_u32 v2, v3, 4, v2
	s_add_u32 s4, s10, s16
	s_addc_u32 s5, s11, s17
	s_add_u32 s4, s4, 0x15800000
	s_addc_u32 s5, s5, 0
	s_waitcnt lgkmcnt(14)
	v_sub_f32_e32 v10, v11, v10
	v_mul_f32_e32 v10, 0x3fb8aa3b, v10
	v_exp_f32_e32 v10, v10
	s_nop 1
	s_waitcnt lgkmcnt(14)
	v_readlane_b32 s32, v10, 0
	v_readlane_b32 s33, v10, 1
	v_readlane_b32 s34, v10, 2
	v_readlane_b32 s35, v10, 3
	v_readlane_b32 s36, v10, 4
	v_readlane_b32 s37, v10, 5
	v_readlane_b32 s38, v10, 6
	v_readlane_b32 s39, v10, 7
	v_lshlrev_b32_e32 v136, 16, v136
	v_lshlrev_b32_e32 v137, 16, v137
	v_lshlrev_b32_e32 v138, 16, v138
	v_lshlrev_b32_e32 v139, 16, v139
	v_lshlrev_b32_e32 v140, 16, v140
	v_lshlrev_b32_e32 v141, 16, v141
	v_lshlrev_b32_e32 v142, 16, v142
	v_lshlrev_b32_e32 v143, 16, v143
	v_mul_f32_e32 v136, s32, v136
	v_mul_f32_e32 v137, s33, v137
	v_mul_f32_e32 v138, s34, v138
	v_mul_f32_e32 v139, s35, v139
	v_mul_f32_e32 v140, s36, v140
	v_mul_f32_e32 v141, s37, v141
	v_mul_f32_e32 v142, s38, v142
	v_mul_f32_e32 v143, s39, v143
	v_cvt_pk_bf16_f32 v12, v136, v137
	v_cvt_pk_bf16_f32 v13, v138, v139
	v_cvt_pk_bf16_f32 v14, v140, v141
	v_cvt_pk_bf16_f32 v15, v142, v143
	global_store_dwordx4 v2, v[12:15], s[4:5] nt
	s_waitcnt lgkmcnt(14)
	v_readlane_b32 s32, v10, 8
	v_readlane_b32 s33, v10, 9
	v_readlane_b32 s34, v10, 10
	v_readlane_b32 s35, v10, 11
	v_readlane_b32 s36, v10, 12
	v_readlane_b32 s37, v10, 13
	v_readlane_b32 s38, v10, 14
	v_readlane_b32 s39, v10, 15
	v_lshlrev_b32_e32 v144, 16, v144
	v_lshlrev_b32_e32 v145, 16, v145
	v_lshlrev_b32_e32 v146, 16, v146
	v_lshlrev_b32_e32 v147, 16, v147
	v_lshlrev_b32_e32 v148, 16, v148
	v_lshlrev_b32_e32 v149, 16, v149
	v_lshlrev_b32_e32 v150, 16, v150
	v_lshlrev_b32_e32 v151, 16, v151
	v_mul_f32_e32 v144, s32, v144
	v_mul_f32_e32 v145, s33, v145
	v_mul_f32_e32 v146, s34, v146
	v_mul_f32_e32 v147, s35, v147
	v_mul_f32_e32 v148, s36, v148
	v_mul_f32_e32 v149, s37, v149
	v_mul_f32_e32 v150, s38, v150
	v_mul_f32_e32 v151, s39, v151
	v_cvt_pk_bf16_f32 v16, v144, v145
	v_cvt_pk_bf16_f32 v17, v146, v147
	v_cvt_pk_bf16_f32 v18, v148, v149
	v_cvt_pk_bf16_f32 v19, v150, v151
	global_store_dwordx4 v2, v[16:19], s[4:5] offset:256 nt
	s_waitcnt lgkmcnt(8)
	v_readlane_b32 s32, v10, 16
	v_readlane_b32 s33, v10, 17
	v_readlane_b32 s34, v10, 18
	v_readlane_b32 s35, v10, 19
	v_readlane_b32 s36, v10, 20
	v_readlane_b32 s37, v10, 21
	v_readlane_b32 s38, v10, 22
	v_readlane_b32 s39, v10, 23
	v_lshlrev_b32_e32 v184, 16, v184
	v_lshlrev_b32_e32 v185, 16, v185
	v_lshlrev_b32_e32 v186, 16, v186
	v_lshlrev_b32_e32 v187, 16, v187
	v_lshlrev_b32_e32 v188, 16, v188
	v_lshlrev_b32_e32 v189, 16, v189
	v_lshlrev_b32_e32 v190, 16, v190
	v_lshlrev_b32_e32 v191, 16, v191
	v_mul_f32_e32 v184, s32, v184
	v_mul_f32_e32 v185, s33, v185
	v_mul_f32_e32 v186, s34, v186
	v_mul_f32_e32 v187, s35, v187
	v_mul_f32_e32 v188, s36, v188
	v_mul_f32_e32 v189, s37, v189
	v_mul_f32_e32 v190, s38, v190
	v_mul_f32_e32 v191, s39, v191
	v_cvt_pk_bf16_f32 v12, v184, v185
	v_cvt_pk_bf16_f32 v13, v186, v187
	v_cvt_pk_bf16_f32 v14, v188, v189
	v_cvt_pk_bf16_f32 v15, v190, v191
	global_store_dwordx4 v2, v[12:15], s[4:5] offset:512 nt
	s_waitcnt lgkmcnt(0)
	v_readlane_b32 s32, v10, 24
	v_readlane_b32 s33, v10, 25
	v_readlane_b32 s34, v10, 26
	v_readlane_b32 s35, v10, 27
	v_readlane_b32 s36, v10, 28
	v_readlane_b32 s37, v10, 29
	v_readlane_b32 s38, v10, 30
	v_readlane_b32 s39, v10, 31
	v_lshlrev_b32_e32 v192, 16, v192
	v_lshlrev_b32_e32 v193, 16, v193
	v_lshlrev_b32_e32 v194, 16, v194
	v_lshlrev_b32_e32 v195, 16, v195
	v_lshlrev_b32_e32 v196, 16, v196
	v_lshlrev_b32_e32 v197, 16, v197
	v_lshlrev_b32_e32 v198, 16, v198
	v_lshlrev_b32_e32 v199, 16, v199
	v_mul_f32_e32 v192, s32, v192
	v_mul_f32_e32 v193, s33, v193
	v_mul_f32_e32 v194, s34, v194
	v_mul_f32_e32 v195, s35, v195
	v_mul_f32_e32 v196, s36, v196
	v_mul_f32_e32 v197, s37, v197
	v_mul_f32_e32 v198, s38, v198
	v_mul_f32_e32 v199, s39, v199
	v_cvt_pk_bf16_f32 v16, v192, v193
	v_cvt_pk_bf16_f32 v17, v194, v195
	v_cvt_pk_bf16_f32 v18, v196, v197
	v_cvt_pk_bf16_f32 v19, v198, v199
	global_store_dwordx4 v2, v[16:19], s[4:5] offset:768 nt
	s_branch .Lpd_done

.Lpe_done:
	s_mov_b64 s[46:47], 0x8000
	s_branch .LBB0_309
.LBB0_550:
	s_waitcnt vmcnt(0)
	s_barrier
	s_mov_b64 s[0:1], exec
	v_readlane_b32 s2, v248, 18
	v_readlane_b32 s3, v248, 19
	s_and_b64 s[2:3], s[0:1], s[2:3]
	s_mov_b64 exec, s[2:3]
	s_cbranch_execz .LBB0_602
	v_readlane_b32 s2, v251, 2
	s_waitcnt vmcnt(0) expcnt(0) lgkmcnt(0)
	s_nop 0
	v_mov_b32_e32 v1, s2
	ds_read_b32 v3, v1
	v_readlane_b32 s2, v251, 3
	s_waitcnt lgkmcnt(0)
	v_cmp_ne_u32_e32 vcc, 0, v3
	v_mov_b32_e32 v1, s2
	ds_read_b32 v2, v1
	s_cbranch_vccnz .LBB0_566
	s_mov_b32 s8, 1
	s_branch .LBB0_554
